# conv boundary fix-up phase: rows of the thread's items touched up front so the dependent load chain hits in L2
# baseline (speedup 1.0000x reference)
; __device__ __forceinline__ void unpack8(const u32x4 w, float (&f)[8]) { f[0] = bf_lo(w.x); f[1] = bf_hi(w.x); f[2] = bf_lo(w.y); f[3] = bf_hi(w.y); f[4] = bf_lo(w.z); f[5] = bf_hi(w.z); f[6] = bf_lo(w.w); f[7] = bf_hi(w.w); }
; __device__ __forceinline__ void phase_fixup(const Args& a) {
;     ...
;     for (int it = blockIdx.x * NT + threadIdx.x; it < total; it += gridDim.x * NT) {
;         const int p = it % 352, rs = it / 352, rho = rs & 1, seg = rs >> 1, j0 = p * 8; const bool first = (seg & 31) == 0; const size_t t = (size_t)seg * 64 + rho;
;         float o[2][8];
; #pragma unroll
;         for (int bj = 0; bj < 2; ++bj) { const int col = bj * DFF + j0;
;             float cur[8], m1[8], m2[8];
;             unpack8(*(const u32x4*)(halo + ((size_t)(seg * 4 + rho) * 2 + bj) * DFF + j0), cur);
; #pragma unroll
;             for (int e = 0; e < 8; ++e) { m1[e] = 0.f; m2[e] = 0.f; }
;             if (rho == 1) { unpack8(*(const u32x4*)(halo + ((size_t)(seg * 4 + 0) * 2 + bj) * DFF + j0), m1);
;                 if (!first) unpack8(*(const u32x4*)(halo + ((size_t)((seg - 1) * 4 + 3) * 2 + bj) * DFF + j0), m2); }
;             else if (!first) { unpack8(*(const u32x4*)(halo + ((size_t)((seg - 1) * 4 + 3) * 2 + bj) * DFF + j0), m1);
;                 unpack8(*(const u32x4*)(halo + ((size_t)((seg - 1) * 4 + 2) * 2 + bj) * DFF + j0), m2); }
.LBB0_816:
	s_or_b64 exec, exec, s[0:1]
	v_readlane_b32 s0, v253, 17
	s_bitcmp0_b32 s0, 8
	s_waitcnt lgkmcnt(0)
	s_barrier
	s_cbranch_scc1 .LBB0_837
	v_lshl_add_u32 v80, s82, 9, v152
	s_mov_b32 s0, 0x58000
	v_cmp_gt_i32_e32 vcc, s0, v80
	s_and_saveexec_b64 s[6:7], vcc
	s_cbranch_execz .LBB0_836
	s_add_u32 s8, s16, 0xa000000
	s_waitcnt vmcnt(8)
	v_lshlrev_b32_e32 v0, 3, v152
	s_addc_u32 s9, s17, 0
	s_lshl_b32 s33, s80, 9
	v_lshl_add_u32 v81, s82, 12, v0
	s_lshl_b32 s38, s80, 12
	s_mov_b64 s[10:11], 0
	s_mov_b32 s39, 0x2e8ba2e9
	s_movk_i32 s40, 0x2c00
	s_mov_b64 s[12:13], 0xb000
	s_mov_b64 s[18:19], 0x5800
	v_mov_b32_e32 v1, 0
	s_mov_b64 s[24:25], 0xdc00
	s_mov_b32 s41, 0xd000
	s_mov_b64 s[26:27], 0x8400
	s_mov_b32 s42, 0x8000
	s_movk_i32 s43, 0x1600
	s_mov_b32 s44, 0x57fff
	v_mov_b32_e32 v128, v80
	v_min_i32_e32 v129, s44, v128
	v_mul_hi_i32 v130, v129, s39
	v_ashrrev_i32_e32 v130, 6, v130
	v_mul_i32_i24_e32 v131, 0x160, v130
	v_sub_u32_e32 v132, v129, v131
	v_lshlrev_b32_e32 v132, 4, v132
	v_mov_b32_e32 v133, 0
	v_lshl_add_u64 v[132:133], v[132:133], 0, s[8:9]
	v_lshlrev_b32_e32 v131, 1, v130
	v_and_b32_e32 v130, 1, v130
	v_sub_u32_e32 v131, v131, v130
	v_mad_i64_i32 v[134:135], vcc, v131, s40, v[132:133]
	global_load_dwordx4 v[136:139], v[134:135], off
	v_add_co_u32_e32 v134, vcc, 0x1600, v134
	s_nop 1
	v_addc_co_u32_e32 v135, vcc, 0, v135, vcc
	global_load_dwordx4 v[136:139], v[134:135], off
	v_add_u32_e32 v131, -1, v131
	v_max_i32_e32 v131, 0, v131
	v_mad_i64_i32 v[134:135], vcc, v131, s40, v[132:133]
	global_load_dwordx4 v[136:139], v[134:135], off
	v_add_co_u32_e32 v134, vcc, 0x1600, v134
	s_nop 1
	v_addc_co_u32_e32 v135, vcc, 0, v135, vcc
	global_load_dwordx4 v[136:139], v[134:135], off
	v_add_u32_e32 v131, -1, v131
	v_max_i32_e32 v131, 0, v131
	v_mad_i64_i32 v[134:135], vcc, v131, s40, v[132:133]
	global_load_dwordx4 v[136:139], v[134:135], off
	v_add_co_u32_e32 v134, vcc, 0x1600, v134
	s_nop 1
	v_addc_co_u32_e32 v135, vcc, 0, v135, vcc
	global_load_dwordx4 v[136:139], v[134:135], off
	v_add_u32_e32 v128, s33, v128
	v_min_i32_e32 v129, s44, v128
	v_mul_hi_i32 v130, v129, s39
	v_ashrrev_i32_e32 v130, 6, v130
	v_mul_i32_i24_e32 v131, 0x160, v130
	v_sub_u32_e32 v132, v129, v131
	v_lshlrev_b32_e32 v132, 4, v132
	v_mov_b32_e32 v133, 0
	v_lshl_add_u64 v[132:133], v[132:133], 0, s[8:9]
	v_lshlrev_b32_e32 v131, 1, v130
	v_and_b32_e32 v130, 1, v130
	v_sub_u32_e32 v131, v131, v130
	v_mad_i64_i32 v[134:135], vcc, v131, s40, v[132:133]
	global_load_dwordx4 v[136:139], v[134:135], off
	v_add_co_u32_e32 v134, vcc, 0x1600, v134
	s_nop 1
	v_addc_co_u32_e32 v135, vcc, 0, v135, vcc
	global_load_dwordx4 v[136:139], v[134:135], off
	v_add_u32_e32 v131, -1, v131
	v_max_i32_e32 v131, 0, v131
	v_mad_i64_i32 v[134:135], vcc, v131, s40, v[132:133]
	global_load_dwordx4 v[136:139], v[134:135], off
	v_add_co_u32_e32 v134, vcc, 0x1600, v134
	s_nop 1
	v_addc_co_u32_e32 v135, vcc, 0, v135, vcc
	global_load_dwordx4 v[136:139], v[134:135], off
	v_add_u32_e32 v131, -1, v131
	v_max_i32_e32 v131, 0, v131
	v_mad_i64_i32 v[134:135], vcc, v131, s40, v[132:133]
	global_load_dwordx4 v[136:139], v[134:135], off
	v_add_co_u32_e32 v134, vcc, 0x1600, v134
	s_nop 1
	v_addc_co_u32_e32 v135, vcc, 0, v135, vcc
	global_load_dwordx4 v[136:139], v[134:135], off
	v_add_u32_e32 v128, s33, v128
	v_min_i32_e32 v129, s44, v128
	v_mul_hi_i32 v130, v129, s39
	v_ashrrev_i32_e32 v130, 6, v130
	v_mul_i32_i24_e32 v131, 0x160, v130
	v_sub_u32_e32 v132, v129, v131
	v_lshlrev_b32_e32 v132, 4, v132
	v_mov_b32_e32 v133, 0
	v_lshl_add_u64 v[132:133], v[132:133], 0, s[8:9]
	v_lshlrev_b32_e32 v131, 1, v130
	v_and_b32_e32 v130, 1, v130
	v_sub_u32_e32 v131, v131, v130
	v_mad_i64_i32 v[134:135], vcc, v131, s40, v[132:133]
	global_load_dwordx4 v[136:139], v[134:135], off
	v_add_co_u32_e32 v134, vcc, 0x1600, v134
	s_nop 1
	v_addc_co_u32_e32 v135, vcc, 0, v135, vcc
	global_load_dwordx4 v[136:139], v[134:135], off
	v_add_u32_e32 v131, -1, v131
	v_max_i32_e32 v131, 0, v131
	v_mad_i64_i32 v[134:135], vcc, v131, s40, v[132:133]
	global_load_dwordx4 v[136:139], v[134:135], off
	v_add_co_u32_e32 v134, vcc, 0x1600, v134
	s_nop 1
	v_addc_co_u32_e32 v135, vcc, 0, v135, vcc
	global_load_dwordx4 v[136:139], v[134:135], off
	v_add_u32_e32 v131, -1, v131
	v_max_i32_e32 v131, 0, v131
	v_mad_i64_i32 v[134:135], vcc, v131, s40, v[132:133]
	global_load_dwordx4 v[136:139], v[134:135], off
	v_add_co_u32_e32 v134, vcc, 0x1600, v134
	s_nop 1
	v_addc_co_u32_e32 v135, vcc, 0, v135, vcc
	global_load_dwordx4 v[136:139], v[134:135], off
	s_branch .LBB0_820
